# v7 + prep weight-transpose tile: 8 row loads and 8 gain loads issued up front, single wait
# speedup vs baseline: 1.0100x; 1.0094x over previous
; DI bool get_trjob(const Params& p, int j, TrJob& o) {
;     ...
;   int nt = N / 64; int kt = t / nt, ntile = t % nt;
;   o.ldsrc = N; o.srccol0 = ntile * 64; o.k0 = kt * 64; o.lddst = K + 64; o.dstrow0 = ntile * 64;
; DI void phase_prep(const Params& p) {
;     ...
;     { int r = tid >> 6, c = tid & 63;
;       for (int i = 0; i < 8; ++i) { int k = i * 8 + r; float v = jb.src[(size_t)(jb.k0 + k) * jb.ldsrc + jb.srccol0 + c]; if (jb.g) v *= jb.g[jb.k0 + k]; tile[k * 65 + c] = v; } }
.LBB0_37:
	s_lshr_b32 s33, s30, 6
	v_cvt_f32_u32_e32 v27, s33
	s_sub_i32 s49, 0, s33
	s_abs_i32 s48, s31
	s_ashr_i32 s42, s31, 31
	v_rcp_iflag_f32_e32 v27, v27
	s_nop 0
	v_mul_f32_e32 v27, 0x4f7ffffe, v27
	v_cvt_u32_f32_e32 v27, v27
	s_nop 0
	v_readfirstlane_b32 s50, v27
	s_mul_i32 s49, s49, s50
	s_mul_hi_u32 s49, s50, s49
	s_add_i32 s50, s50, s49
	s_mul_hi_u32 s49, s48, s50
	s_mul_i32 s50, s49, s33
	s_sub_i32 s48, s48, s50
	s_add_i32 s51, s49, 1
	s_sub_i32 s50, s48, s33
	s_cmp_ge_u32 s48, s33
	s_cselect_b32 s49, s51, s49
	s_cselect_b32 s48, s50, s48
	s_add_i32 s50, s49, 1
	s_cmp_ge_u32 s48, s33
	s_cselect_b32 s48, s50, s49
	s_xor_b32 s48, s48, s42
	s_sub_i32 s42, s48, s42
	s_mul_i32 s33, s42, s33
	s_sub_i32 s31, s31, s33
	s_lshl_b32 s50, s31, 6
	s_ashr_i32 s51, s50, 31
	s_lshl_b32 s48, s42, 6
	s_lshl_b64 s[52:53], s[50:51], 2
	s_add_u32 s6, s6, s52
	v_add_u32_e32 v32, s48, v1
	s_addc_u32 s7, s7, s53
	v_lshl_add_u64 v[30:31], s[6:7], 0, v[8:9]
	v_mad_u64_u32 v[34:35], s[6:7], v32, s30, 0
	v_ashrrev_i32_e32 v33, 31, v32
	v_mov_b32_e32 v40, v35
	v_mad_u64_u32 v[40:41], s[6:7], v33, s30, v[40:41]
	v_mov_b32_e32 v35, v40
	v_lshl_add_u64 v[34:35], v[34:35], 2, v[30:31]
	v_mov_b64_e32 v[236:237], v[34:35]
	s_lshl_b32 s52, s30, 5
	s_mov_b32 s53, 0
	global_load_dword v220, v[236:237], off
	v_lshl_add_u64 v[236:237], v[236:237], 0, s[52:53]
	global_load_dword v221, v[236:237], off
	v_lshl_add_u64 v[236:237], v[236:237], 0, s[52:53]
	global_load_dword v222, v[236:237], off
	v_lshl_add_u64 v[236:237], v[236:237], 0, s[52:53]
	global_load_dword v223, v[236:237], off
	v_lshl_add_u64 v[236:237], v[236:237], 0, s[52:53]
	global_load_dword v224, v[236:237], off
	v_lshl_add_u64 v[236:237], v[236:237], 0, s[52:53]
	global_load_dword v225, v[236:237], off
	v_lshl_add_u64 v[236:237], v[236:237], 0, s[52:53]
	global_load_dword v226, v[236:237], off
	v_lshl_add_u64 v[236:237], v[236:237], 0, s[52:53]
	global_load_dword v227, v[236:237], off
	s_cmp_eq_u64 s[46:47], 0
	v_lshl_add_u64 v[34:35], v[32:33], 2, s[46:47]
	s_cbranch_scc1 .Lprep_tr_nog
	global_load_dword v228, v[34:35], off
	global_load_dword v229, v[34:35], off offset:32
	global_load_dword v230, v[34:35], off offset:64
	global_load_dword v231, v[34:35], off offset:96
	global_load_dword v232, v[34:35], off offset:128
	global_load_dword v233, v[34:35], off offset:160
	global_load_dword v234, v[34:35], off offset:192
	global_load_dword v235, v[34:35], off offset:224
	s_waitcnt vmcnt(0)
	v_mul_f32_e32 v220, v220, v228
	v_mul_f32_e32 v221, v221, v229
	v_mul_f32_e32 v222, v222, v230
	v_mul_f32_e32 v223, v223, v231
	v_mul_f32_e32 v224, v224, v232
	v_mul_f32_e32 v225, v225, v233
	v_mul_f32_e32 v226, v226, v234
	v_mul_f32_e32 v227, v227, v235
.Lprep_tr_nog:
	s_waitcnt vmcnt(0)
	ds_write_b32 v38, v220
	ds_write_b32 v38, v221 offset:2080
	ds_write_b32 v38, v222 offset:4160
	ds_write_b32 v38, v223 offset:6240
	ds_write_b32 v38, v224 offset:8320
	ds_write_b32 v38, v225 offset:10400
	ds_write_b32 v38, v226 offset:12480
	v_mov_b32_e32 v30, v227
	s_branch .LBB0_8
